# attention unit prologue: removed drain of Q loads before first K/V LDS-DMA issue (counted waits already cover Q)
# baseline (speedup 1.0000x reference)
; __device__ __forceinline__ int v_rd_base(int lane) { return ((lane & 3) << 3) | (((lane >> 2) & 3) << 6) | (((lane >> 4) & 1) << 5) | (((lane >> 5) & 1) << 8); }
; #define WAIT_BAR(N) asm volatile("s_waitcnt vmcnt(" #N ") lgkmcnt(0)\n\ts_barrier" ::: "memory")
; #define DMA_K(t, slot) do { const bf16* kb_ = Kh + (long)(t) * KVBLK * LDP; glds16(kb_, kofs[0], kdst + (slot) * SHM_K); glds16(kb_, kofs[1], kdst + (slot) * SHM_K + 8192); } while (0)
; #define DMA_V(t, slot) do { const bf16* vb_ = Vh + (long)(t) * KVBLK * LDP; glds16(vb_, vofs[0], vdst + (slot) * SHM_V); glds16(vb_, vofs[1], vdst + (slot) * SHM_V + 8192); } while (0)
; __device__ __forceinline__ void attn_unit(const bf16* __restrict__ proj, bf16* __restrict__ cat, int b, int h, int qb, float lam, float oscale, const float* __restrict__ subln, const float* __restrict__ cw, char* lds) {
;     ...
;   const bf16* Qw = proj + (rowbase + qb * QROWS + rg * 32 + r32) * LDP + (2 * h + mp) * 64 + hi * 8;
; #pragma unroll
;   for (int d0 = 0; d0 < 4; ++d0) qr[d0] = *reinterpret_cast<const bf16x8*>(Qw + d0 * 16);
;   const int cbase = mp * 128;
;   unsigned kofs[2], vofs[2];
; #pragma unroll
;   for (int i = 0; i < 2; ++i) { const int q = wid + 8 * i, p = 64 * q + lane;
;     const int krow = p >> 4, kc8 = (p & 15) ^ (krow & 15); kofs[i] = (unsigned)(krow * LDP + kc8 * 8) * 2u;
;     const int kk = (p >> 7) * 8 + ((p & 31) >> 2), c = ((p >> 5) & 3) * 32 + (p & 3) * 8, k = (kk & ~0xC) | ((kk & 4) << 1) | ((kk & 8) >> 1); vofs[i] = (unsigned)(k * LDP + c) * 2u; }
;   const unsigned lds0 = (unsigned)(uintptr_t)lds, kdst = lds0 + wid * 1024, vdst = lds0 + 3 * SHM_K + wid * 1024;
;     ...
;   const int vb0 = (int)(lds0 + 3 * SHM_K) + v_rd_base(lane);
;     ...
;   f32x16 pA0, pA1, pB0, pB1; float mnA, mnB, alA, alB; bf16x8 pa0, pa1, pa2, pa3; constexpr int NT = SEQ / KVBLK;
;   asm volatile("s_waitcnt vmcnt(0)" ::: "memory");
;   DMA_K(0, 0); DMA_V(0, 0); DMA_K(1, 1);
;   WAIT_BAR(2);
;   qkt(pA0, pA1, K_lds, qr, r32, hi, cbase); partialSM(pA0, pA1, m_reg, mnA, alA);
.Latt_noprio:
	s_add_i32 s70, s70, 0x18000
	s_lshl_b64 s[44:45], s[46:47], 12
	s_mul_i32 s21, s46, 0x3000000
	s_mul_hi_i32 s20, s46, 0x3000000
	s_add_u32 s46, s66, s21
	s_addc_u32 s47, s67, s20
	s_lshl_b32 s38, s38, 7
	s_and_b32 s38, s38, 0xf80
	s_or_b32 s38, s44, s38
	s_lshl_b32 s39, s25, 5
	v_and_b32_e32 v174, 31, v8
	s_or_b32 s44, s38, s39
	v_or_b32_e32 v2, s44, v174
	v_mov_b64_e32 v[0:1], s[66:67]
	s_lshl_b32 s28, s73, 7
	v_mad_u64_u32 v[0:1], s[38:39], v2, s1, v[0:1]
	s_and_b32 s28, s28, 0x380
	s_lshl_b32 s38, s24, 6
	s_add_i32 s38, s38, s28
	v_bfe_u32 v179, v8, 5, 1
	v_mad_i32_i24 v1, s45, v200, v1
	s_ashr_i32 s39, s38, 31
	v_lshl_add_u64 v[0:1], s[38:39], 1, v[0:1]
	v_lshlrev_b32_e32 v162, 4, v179
	v_lshl_add_u64 v[0:1], v[0:1], 0, v[162:163]
	global_load_dwordx4 v[140:143], v[0:1], off
	global_load_dwordx4 v[136:139], v[0:1], off offset:32
	global_load_dwordx4 v[132:135], v[0:1], off offset:64
	global_load_dwordx4 v[128:131], v[0:1], off offset:96
	s_lshl_b32 s38, s28, 1
	s_add_u32 s75, s46, s38
	v_mov_b32_e32 v2, s31
	s_movk_i32 s38, 0xffc0
	s_addc_u32 s77, s47, 0
	v_bfi_b32 v2, s38, v2, v8
	s_add_u32 s46, s75, 0x1000
	v_ashrrev_i32_e32 v2, 4, v2
	s_addc_u32 s47, s77, 0
	v_xor_b32_e32 v3, v2, v8
	s_ashr_i32 s38, s71, 4
	v_mul_lo_u32 v2, v2, s33
	v_lshlrev_b32_e32 v3, 3, v3
	s_and_b32 s39, s38, 0x1ffff0
	s_lshr_b32 s38, s38, 1
	v_and_b32_e32 v177, 63, v8
	v_bfe_u32 v0, v8, 2, 3
	v_lshrrev_b32_e32 v180, 1, v8
	v_and_or_b32 v2, v3, s0, v2
	s_and_b32 s38, s38, 4
	v_lshlrev_b32_e32 v184, 1, v2
	v_bitop3_b32 v2, s71, v201, v177 bitop3:0xc8
	s_lshr_b32 s38, s71, 7
	s_lshl_b32 s38, s38, 3
	s_addk_i32 s71, 0x200
	v_lshlrev_b32_e32 v178, 3, v8
	v_or_b32_e32 v3, s38, v0
	s_ashr_i32 s38, s71, 4
	v_and_b32_e32 v1, 24, v178
	v_mul_u32_u24_e32 v3, 0x1800, v3
	s_and_b32 s39, s38, 0x1ffff0
	s_lshr_b32 s38, s38, 1
	v_or3_b32 v2, v3, v2, v1
	s_and_b32 s38, s38, 4
	v_lshlrev_b32_e32 v185, 1, v2
	v_or_b32_e32 v2, s71, v177
	s_lshr_b32 s38, s71, 7
	s_lshl_b32 s38, s38, 3
	v_ashrrev_i32_e32 v2, 4, v2
	s_add_u32 s78, s75, 0x800
	v_xor_b32_e32 v3, v2, v8
	s_addc_u32 s79, s77, 0
	s_lshl_b32 s39, s24, 7
	s_lshl_b32 s72, s29, 10
	v_mul_lo_u32 v2, v2, s33
	v_lshlrev_b32_e32 v3, 3, v3
	s_cmp_lg_u32 0, -1
	v_and_or_b32 v2, v3, s0, v2
	v_or_b32_e32 v0, s38, v0
	s_cselect_b32 s38, 0, 0
	s_nop 0
	v_lshlrev_b32_e32 v186, 1, v2
	v_bitop3_b32 v2, s71, v201, v177 bitop3:0xc8
	s_add_i32 s71, s72, s38
	s_mov_b32 s74, m0
	s_mov_b32 m0, s71
	s_nop 0
	global_load_lds_dwordx4 v184, s[78:79]
	s_mov_b32 m0, s74
	s_add_i32 s38, s38, 0xc000
	s_add_i32 s74, s71, 0x2000
	s_mov_b32 s76, m0
	s_mov_b32 m0, s74
	s_nop 0
	global_load_lds_dwordx4 v186, s[78:79]
	s_mov_b32 m0, s76
	v_mul_u32_u24_e32 v0, 0x1800, v0
	s_add_i32 s72, s72, s38
	s_mov_b32 s74, m0
	s_mov_b32 m0, s72
	s_nop 0
	global_load_lds_dwordx4 v185, s[46:47]
	s_mov_b32 m0, s74
	v_or3_b32 v0, v0, v2, v1
	s_add_i32 s74, s71, 0xe000
	v_lshlrev_b32_e32 v187, 1, v0
	v_lshlrev_b32_e32 v9, 4, v8
	s_mov_b32 s76, m0
	s_mov_b32 m0, s74
	s_nop 0
	global_load_lds_dwordx4 v187, s[46:47]
	s_mov_b32 m0, s76
	s_add_u32 s46, s75, 0xc0800
	s_addc_u32 s47, s77, 0
	s_add_i32 s74, s71, 0x4000
	s_mov_b32 s76, m0
	s_mov_b32 m0, s74
	s_nop 0
	global_load_lds_dwordx4 v184, s[46:47]
	s_mov_b32 m0, s76
	v_and_b32_e32 v10, 0xf0, v9
	s_add_i32 s74, s71, 0x6000
	s_mov_b32 s76, m0
	s_mov_b32 m0, s74
	s_nop 0
	global_load_lds_dwordx4 v186, s[46:47]
	s_mov_b32 m0, s76
	v_lshl_add_u32 v189, v174, 8, 0
	v_bitop3_b32 v210, s39, v10, v162 bitop3:0x36
	s_waitcnt vmcnt(2) lgkmcnt(0)
	s_barrier
	v_add_u32_e32 v188, v189, v210
	ds_read_b128 v[0:3], v188
	ds_read_b128 v[4:7], v188 offset:8192
	s_waitcnt vmcnt(3) lgkmcnt(1)
	v_mfma_f32_32x32x16_bf16 v[32:47], v[0:3], v[140:143], 0
	v_or_b32_e32 v11, s39, v162
	v_bitop3_b32 v212, v11, v10, 32 bitop3:0x36
	v_add_u32_e32 v211, v189, v212
	v_bitop3_b32 v214, v11, v10, 64 bitop3:0x36
	v_add_u32_e32 v213, v189, v214
	s_movk_i32 s39, 0x60
	v_lshlrev_b32_e32 v181, 3, v177
	s_waitcnt lgkmcnt(0)
	v_mfma_f32_32x32x16_bf16 v[16:31], v[4:7], v[140:143], 0
	ds_read_b128 v[0:3], v211
	ds_read_b128 v[4:7], v211 offset:8192
	v_bitop3_b32 v216, v11, v10, s39 bitop3:0x36
	v_add_u32_e32 v215, v189, v216
	ds_read_b128 v[48:51], v215 offset:8192
	v_readlane_b32 s80, v255, 8
	s_mov_b32 s8, s80
	v_readlane_b32 s81, v255, 9
	s_waitcnt vmcnt(2) lgkmcnt(2)
	v_mfma_f32_32x32x16_bf16 v[32:47], v[0:3], v[136:139], v[32:47]
	ds_read_b128 v[0:3], v213
	v_readlane_b32 s82, v255, 10
	v_readlane_b32 s83, v255, 11
	v_readlane_b32 s84, v255, 12
	v_readlane_b32 s85, v255, 13
	v_readlane_b32 s86, v255, 14
	v_readlane_b32 s87, v255, 15
	s_waitcnt lgkmcnt(2)
	v_mfma_f32_32x32x16_bf16 v[16:31], v[4:7], v[136:139], v[16:31]
	v_and_b32_e32 v4, 0xc0, v9
	v_and_or_b32 v9, v181, 24, v4
	v_lshlrev_b32_e32 v4, 1, v8
	v_and_b32_e32 v8, 32, v4
	ds_read_b128 v[4:7], v213 offset:8192
	v_readlane_b32 s88, v255, 16
	v_readlane_b32 s89, v255, 17
	s_waitcnt vmcnt(1) lgkmcnt(1)
	v_mfma_f32_32x32x16_bf16 v[32:47], v[0:3], v[132:135], v[32:47]
	ds_read_b128 v[0:3], v215
	v_readlane_b32 s90, v255, 18
	v_readlane_b32 s91, v255, 19
	v_readlane_b32 s92, v255, 20
	v_readlane_b32 s93, v255, 21
	v_readlane_b32 s94, v255, 22
	v_readlane_b32 s95, v255, 23
	s_waitcnt lgkmcnt(1)
	v_mfma_f32_32x32x16_bf16 v[16:31], v[4:7], v[132:135], v[16:31]
	v_writelane_b32 v255, s8, 8
	v_and_b32_e32 v12, 0x100, v181
	v_or3_b32 v183, v9, v8, v12
	v_writelane_b32 v255, s9, 9
	v_writelane_b32 v255, s10, 10
	v_writelane_b32 v255, s11, 11
	v_writelane_b32 v255, s12, 12
	s_waitcnt vmcnt(0) lgkmcnt(0)
; #define WAIT_BAR(N) asm volatile("s_waitcnt vmcnt(" #N ") lgkmcnt(0)\n\ts_barrier" ::: "memory")
; #define DMA_K(t, slot) do { const bf16* kb_ = Kh + (long)(t) * KVBLK * LDP; glds16(kb_, kofs[0], kdst + (slot) * SHM_K); glds16(kb_, kofs[1], kdst + (slot) * SHM_K + 8192); } while (0)
; #define DMA_V(t, slot) do { const bf16* vb_ = Vh + (long)(t) * KVBLK * LDP; glds16(vb_, vofs[0], vdst + (slot) * SHM_V); glds16(vb_, vofs[1], vdst + (slot) * SHM_V + 8192); } while (0)
; __device__ __forceinline__ void partialSM(f32x16& p0, f32x16& p1, float& m_reg, float& mn, float& alpha) {
;   float pmax = p0[0];
; #pragma unroll
;   for (int r = 1; r < 16; ++r) pmax = fmaxf(pmax, p0[r]);
; #pragma unroll
;   for (int r = 0; r < 16; ++r) pmax = fmaxf(pmax, p1[r]);
;   { auto rr = __builtin_amdgcn_permlane32_swap(__float_as_uint(pmax), __float_as_uint(pmax), false, false);
;     pmax = fmaxf(__uint_as_float(rr[0]), __uint_as_float(rr[1])); }
;   if (__builtin_expect(__all(pmax - m_reg <= THR), 1)) { mn = m_reg; alpha = 1.f; }
;   else { mn = fmaxf(m_reg, pmax); alpha = __builtin_amdgcn_exp2f(m_reg - mn); m_reg = mn; }
; #pragma unroll
;   for (int r = 0; r < 16; ++r) p0[r] = p0[r] - mn;
; #pragma unroll
;   for (int r = 0; r < 16; ++r) p1[r] = p1[r] - mn;
; #pragma unroll
;   for (int r = 0; r < 16; ++r) p0[r] = __builtin_amdgcn_exp2f(p0[r]);
; }
; __device__ __forceinline__ void attn_unit(const bf16* __restrict__ proj, bf16* __restrict__ cat, int b, int h, int qb, float lam, float oscale, const float* __restrict__ subln, const float* __restrict__ cw, char* lds) {
;     ...
;   qkt(pA0, pA1, K_lds, qr, r32, hi, cbase); partialSM(pA0, pA1, m_reg, mnA, alA);
; #pragma unroll
;   for (int r = 0; r < 16; ++r) pA1[r] = __builtin_amdgcn_exp2f(pA1[r]);
;   DMA_V(1, 1); DMA_K(2, 2);
;   WAIT_BAR(4);
	v_mfma_f32_32x32x16_bf16 v[32:47], v[0:3], v[128:131], v[32:47]
	v_writelane_b32 v255, s13, 13
	v_writelane_b32 v255, s14, 14
	v_writelane_b32 v255, s15, 15
	v_add_u32_e32 v217, s38, v183
	v_writelane_b32 v255, s16, 16
	v_writelane_b32 v255, s17, 17
	v_writelane_b32 v255, s18, 18
	v_mfma_f32_32x32x16_bf16 v[16:31], v[48:51], v[128:131], v[16:31]
	s_nop 3
	v_max_f32_e32 v48, v33, v33
	v_max_f32_e32 v49, v32, v32
	v_max_f32_e32 v48, v49, v48
	v_max3_f32 v48, v48, v34, v35
	v_max3_f32 v48, v48, v36, v37
	v_max3_f32 v48, v48, v38, v39
	v_max3_f32 v48, v48, v40, v41
	v_max3_f32 v48, v48, v42, v43
	v_max3_f32 v48, v48, v44, v45
	v_max3_f32 v48, v48, v46, v47
	v_max3_f32 v48, v48, v16, v17
	v_max3_f32 v48, v48, v18, v19
	v_max3_f32 v48, v48, v20, v21
	v_max3_f32 v48, v48, v22, v23
	v_max3_f32 v48, v48, v24, v25
	v_max3_f32 v48, v48, v26, v27
	v_max3_f32 v48, v48, v28, v29
	v_max3_f32 v48, v48, v30, v31
	v_mov_b32_e32 v49, v48
	s_nop 1
	v_permlane32_swap_b32_e32 v48, v49
	v_max_f32_e32 v49, v49, v49
	v_max_f32_e32 v48, v48, v48
	v_max_f32_e32 v48, v48, v49
	v_add_f32_e32 v49, 0x7149f2ca, v48
	v_cmp_ge_f32_e32 vcc, s6, v49
	s_cmp_eq_u64 vcc, exec
	s_cselect_b64 vcc, -1, 0
	s_add_u32 s38, s75, 0xc1000
	s_addc_u32 s39, s77, 0
	s_add_i32 s46, s71, 0x10000
	s_mov_b32 s47, m0
	s_mov_b32 m0, s46
	s_nop 0
	global_load_lds_dwordx4 v185, s[38:39]
	s_mov_b32 m0, s47
	s_add_i32 s46, s71, 0x12000
	s_mov_b32 s47, m0
	s_mov_b32 m0, s46
	s_nop 0
	global_load_lds_dwordx4 v187, s[38:39]
	s_mov_b32 m0, s47
	s_add_u32 s38, s75, 0x180800
	v_writelane_b32 v255, s19, 19
	v_max_f32_e32 v48, 0xf149f2ca, v48
	s_addc_u32 s39, s77, 0
	s_add_i32 s46, s71, 0x8000
	v_writelane_b32 v255, s20, 20
	v_cndmask_b32_e32 v218, v48, v202, vcc
	s_mov_b32 s47, m0
	s_mov_b32 m0, s46
	s_nop 0
	global_load_lds_dwordx4 v184, s[38:39]
	s_mov_b32 m0, s47
	s_add_i32 s46, s71, 0xa000
	v_writelane_b32 v255, s21, 21
	v_sub_f32_e32 v49, 0xf149f2ca, v48
	v_sub_f32_e32 v16, v16, v218
	s_mov_b32 s47, m0
	s_mov_b32 m0, s46
	s_nop 0
	global_load_lds_dwordx4 v186, s[38:39]
	s_mov_b32 m0, s47
	s_and_b32 s46, s73, 7
	v_writelane_b32 v255, s22, 22
	v_exp_f32_e32 v64, v16
	v_exp_f32_e32 v16, v49
	s_lshl_b32 s46, s46, 8
	s_mov_b32 s81, s80
	v_writelane_b32 v255, s23, 23
	v_sub_f32_e32 v32, v32, v218
	v_sub_f32_e32 v33, v33, v218
	v_sub_f32_e32 v34, v34, v218
	v_sub_f32_e32 v35, v35, v218
	v_sub_f32_e32 v36, v36, v218
	v_sub_f32_e32 v37, v37, v218
	v_sub_f32_e32 v38, v38, v218
	v_sub_f32_e32 v39, v39, v218
	v_sub_f32_e32 v40, v40, v218
	v_sub_f32_e32 v41, v41, v218
	v_sub_f32_e32 v42, v42, v218
	v_sub_f32_e32 v43, v43, v218
	v_sub_f32_e32 v44, v44, v218
	v_sub_f32_e32 v45, v45, v218
	v_sub_f32_e32 v46, v46, v218
	v_sub_f32_e32 v47, v47, v218
	v_sub_f32_e32 v17, v17, v218
	v_sub_f32_e32 v18, v18, v218
	v_sub_f32_e32 v19, v19, v218
	v_sub_f32_e32 v20, v20, v218
	v_sub_f32_e32 v21, v21, v218
	v_sub_f32_e32 v22, v22, v218
	v_sub_f32_e32 v23, v23, v218
	v_sub_f32_e32 v24, v24, v218
	v_sub_f32_e32 v25, v25, v218
	v_sub_f32_e32 v26, v26, v218
	v_sub_f32_e32 v27, v27, v218
	v_sub_f32_e32 v28, v28, v218
	v_sub_f32_e32 v29, v29, v218
	v_sub_f32_e32 v30, v30, v218
	v_sub_f32_e32 v31, v31, v218
	s_or_b32 s21, s21, s46
	s_mov_b32 s82, s80
	s_mov_b32 s83, s80
	s_mov_b32 s84, s80
	s_mov_b32 s85, s80
	s_mov_b32 s86, s80
	s_mov_b32 s87, s80
	s_mov_b32 s88, s80
	s_mov_b32 s89, s80
	s_mov_b32 s90, s80
	s_mov_b32 s91, s80
	s_mov_b32 s92, s80
	s_mov_b32 s93, s80
	s_mov_b32 s94, s80
	s_mov_b32 s95, s80
	v_mov_b64_e32 v[0:1], s[80:81]
	v_exp_f32_e32 v80, v32
	v_exp_f32_e32 v81, v33
	v_exp_f32_e32 v82, v34
	v_exp_f32_e32 v83, v35
	v_exp_f32_e32 v84, v36
	v_exp_f32_e32 v85, v37
	v_exp_f32_e32 v86, v38
	v_exp_f32_e32 v87, v39
	v_exp_f32_e32 v88, v40
	v_exp_f32_e32 v89, v41
	v_exp_f32_e32 v90, v42
	v_exp_f32_e32 v91, v43
	v_exp_f32_e32 v92, v44
	v_exp_f32_e32 v93, v45
	v_exp_f32_e32 v94, v46
	v_exp_f32_e32 v95, v47
	v_exp_f32_e32 v65, v17
	v_exp_f32_e32 v66, v18
	v_exp_f32_e32 v67, v19
	v_exp_f32_e32 v68, v20
	v_exp_f32_e32 v69, v21
	v_exp_f32_e32 v70, v22
	v_exp_f32_e32 v71, v23
	v_exp_f32_e32 v72, v24
	v_exp_f32_e32 v73, v25
	v_exp_f32_e32 v74, v26
	v_exp_f32_e32 v75, v27
	v_exp_f32_e32 v76, v28
	v_exp_f32_e32 v77, v29
	v_exp_f32_e32 v78, v30
	v_exp_f32_e32 v79, v31
	s_add_u32 s73, s3, s21
	v_mov_b64_e32 v[14:15], s[94:95]
	s_waitcnt vmcnt(4) lgkmcnt(0)
	s_barrier
; __device__ __forceinline__ int v_rd_base(int lane) { return ((lane & 3) << 3) | (((lane >> 2) & 3) << 6) | (((lane >> 4) & 1) << 5) | (((lane >> 5) & 1) << 8); }
; #define WAIT_BAR(N) asm volatile("s_waitcnt vmcnt(" #N ") lgkmcnt(0)\n\ts_barrier" ::: "memory")
; #define DMA_K(t, slot) do { const bf16* kb_ = Kh + (long)(t) * KVBLK * LDP; glds16(kb_, kofs[0], kdst + (slot) * SHM_K); glds16(kb_, kofs[1], kdst + (slot) * SHM_K + 8192); } while (0)
; #define DMA_V(t, slot) do { const bf16* vb_ = Vh + (long)(t) * KVBLK * LDP; glds16(vb_, vofs[0], vdst + (slot) * SHM_V); glds16(vb_, vofs[1], vdst + (slot) * SHM_V + 8192); } while (0)
; __device__ __forceinline__ void attn_unit(const bf16* __restrict__ proj, bf16* __restrict__ cat, int b, int h, int qb, float lam, float oscale, const float* __restrict__ subln, const float* __restrict__ cw, char* lds) {
;     ...
;   float m_reg = -1e30f, l_reg = 0; f32x16 o[4] = {}; bf16x8 qr[4];
;   const bf16* Qw = proj + (rowbase + qb * QROWS + rg * 32 + r32) * LDP + (2 * h + mp) * 64 + hi * 8;
; #pragma unroll
;   for (int d0 = 0; d0 < 4; ++d0) qr[d0] = *reinterpret_cast<const bf16x8*>(Qw + d0 * 16);
;   const int cbase = mp * 128;
;   unsigned kofs[2], vofs[2];
; #pragma unroll
;   for (int i = 0; i < 2; ++i) { const int q = wid + 8 * i, p = 64 * q + lane;
;     const int krow = p >> 4, kc8 = (p & 15) ^ (krow & 15); kofs[i] = (unsigned)(krow * LDP + kc8 * 8) * 2u;
;     const int kk = (p >> 7) * 8 + ((p & 31) >> 2), c = ((p >> 5) & 3) * 32 + (p & 3) * 8, k = (kk & ~0xC) | ((kk & 4) << 1) | ((kk & 8) >> 1); vofs[i] = (unsigned)(k * LDP + c) * 2u; }
;   const unsigned lds0 = (unsigned)(uintptr_t)lds, kdst = lds0 + wid * 1024, vdst = lds0 + 3 * SHM_K + wid * 1024;
;     ...
;   const int vb0 = (int)(lds0 + 3 * SHM_K) + v_rd_base(lane);
;     ...
;   f32x16 pA0, pA1, pB0, pB1; float mnA, mnB, alA, alB; bf16x8 pa0, pa1, pa2, pa3; constexpr int NT = SEQ / KVBLK;
;   asm volatile("s_waitcnt vmcnt(0)" ::: "memory");
;   DMA_K(0, 0); DMA_V(0, 0); DMA_K(1, 1);
;   WAIT_BAR(2);
;   qkt(pA0, pA1, K_lds, qr, r32, hi, cbase); partialSM(pA0, pA1, m_reg, mnA, alA);
; #pragma unroll
;   for (int r = 0; r < 16; ++r) pA1[r] = __builtin_amdgcn_exp2f(pA1[r]);
;   DMA_V(1, 1); DMA_K(2, 2);
;   WAIT_BAR(4);
;   int sj = 1;
	s_addc_u32 s74, s62, s20
	v_mov_b64_e32 v[2:3], s[82:83]
	v_mov_b64_e32 v[4:5], s[84:85]
	v_mov_b64_e32 v[6:7], s[86:87]
	v_mov_b64_e32 v[8:9], s[88:89]
	v_mov_b64_e32 v[10:11], s[90:91]
	v_mov_b64_e32 v[12:13], s[92:93]
	v_cndmask_b32_e64 v220, v16, 1.0, vcc
	s_add_u32 s82, s75, 0x240800
	v_mov_b64_e32 v[62:63], v[14:15]
	v_mov_b64_e32 v[46:47], v[14:15]
	v_mov_b64_e32 v[30:31], v[14:15]
	s_mov_b32 s76, 1
	v_cmp_gt_u32_e64 s[38:39], 32, v177
	v_lshl_add_u32 v182, v174, 2, s70
	s_addc_u32 s83, s77, 0
	v_mov_b32_e32 v219, 0
	v_mov_b64_e32 v[60:61], v[12:13]
	v_mov_b64_e32 v[58:59], v[10:11]
	v_mov_b64_e32 v[56:57], v[8:9]
	v_mov_b64_e32 v[54:55], v[6:7]
	v_mov_b64_e32 v[52:53], v[4:5]
	v_mov_b64_e32 v[50:51], v[2:3]
	v_mov_b64_e32 v[48:49], v[0:1]
	v_mov_b64_e32 v[44:45], v[12:13]
	v_mov_b64_e32 v[42:43], v[10:11]
	v_mov_b64_e32 v[40:41], v[8:9]
	v_mov_b64_e32 v[38:39], v[6:7]
	v_mov_b64_e32 v[36:37], v[4:5]
	v_mov_b64_e32 v[34:35], v[2:3]
	v_mov_b64_e32 v[32:33], v[0:1]
	v_mov_b64_e32 v[28:29], v[12:13]
	v_mov_b64_e32 v[26:27], v[10:11]
	v_mov_b64_e32 v[24:25], v[8:9]
	v_mov_b64_e32 v[22:23], v[6:7]
	v_mov_b64_e32 v[20:21], v[4:5]
	v_mov_b64_e32 v[18:19], v[2:3]
	v_mov_b64_e32 v[16:17], v[0:1]
	s_mov_b32 s75, 1
	v_add_f32_e32 v196, v80, v81
	v_add_f32_e32 v196, v82, v196
	v_add_f32_e32 v196, v83, v196
	v_add_f32_e32 v196, v84, v196
	v_add_f32_e32 v196, v85, v196
	v_add_f32_e32 v196, v86, v196
	v_add_f32_e32 v196, v87, v196
	v_add_f32_e32 v196, v88, v196
	v_add_f32_e32 v196, v89, v196
	v_add_f32_e32 v196, v90, v196
	v_add_f32_e32 v196, v91, v196
	v_add_f32_e32 v196, v92, v196
	v_add_f32_e32 v196, v93, v196
	v_add_f32_e32 v196, v94, v196
	v_add_f32_e32 v196, v95, v196
	v_add_f32_e32 v196, v64, v196
	v_add_f32_e32 v196, v65, v196
	v_add_f32_e32 v196, v66, v196
	v_add_f32_e32 v196, v67, v196
	v_add_f32_e32 v196, v68, v196
	v_add_f32_e32 v196, v69, v196
	v_add_f32_e32 v196, v70, v196
	v_add_f32_e32 v196, v71, v196
	v_add_f32_e32 v196, v72, v196
	v_add_f32_e32 v196, v73, v196
	v_add_f32_e32 v196, v74, v196
	v_add_f32_e32 v196, v75, v196
	v_add_f32_e32 v196, v76, v196
	v_add_f32_e32 v196, v77, v196
	v_add_f32_e32 v196, v78, v196
	v_add_f32_e32 v196, v79, v196
	s_lshl_b32 s20, s24, 2
	s_add_i32 s20, s20, s25
	s_mul_i32 s20, s20, 0x600
	s_add_i32 s20, s20, 0x18800
	v_lshl_add_u32 v197, v177, 2, s20
	ds_write_b32 v197, v174
	ds_write_b32 v197, v175 offset:256
	ds_write_b32 v197, v176 offset:512
	ds_write_b32 v197, v177 offset:768
	ds_write_b32 v197, v178 offset:1024
	ds_write_b32 v197, v179 offset:1280
	s_waitcnt lgkmcnt(0)
	v_xor_b32_e32 v164, 0x80000000, v218
	v_xor_b32_e32 v165, 0x80000000, v218
	v_xor_b32_e32 v166, 0x80000000, v218
	v_xor_b32_e32 v167, 0x80000000, v218
	v_xor_b32_e32 v168, 0x80000000, v218
	v_xor_b32_e32 v169, 0x80000000, v218
	v_xor_b32_e32 v170, 0x80000000, v218
	v_xor_b32_e32 v171, 0x80000000, v218
	v_xor_b32_e32 v172, 0x80000000, v218
	v_xor_b32_e32 v173, 0x80000000, v218
	v_xor_b32_e32 v174, 0x80000000, v218
	v_xor_b32_e32 v175, 0x80000000, v218
	v_xor_b32_e32 v176, 0x80000000, v218
	v_xor_b32_e32 v177, 0x80000000, v218
	v_xor_b32_e32 v178, 0x80000000, v218
	v_xor_b32_e32 v179, 0x80000000, v218
	s_branch .LBB0_218
